# bundle: conv GLU staging loads batched, entry cooperative-groups sync skipped (census barrier suffices)
# speedup vs baseline: 1.0172x; 1.0123x over previous
; #define LAS __attribute__((address_space(3)))
; __global__ void __launch_bounds__(NTHR, 2) mega_fwd(Args args) {
;     ...
;     cg::grid_group grid = cg::this_grid();
;     if (threadIdx.x < 32) ((LAS unsigned*)((LAS unsigned char*)lds + MISC_OFF))[threadIdx.x] = 0u;
;     __syncthreads();
;     XcdBarrier xbar = xcd_barrier_post((unsigned*)((unsigned char*)kargp(25) + WS_CTL), (volatile LAS unsigned*)((LAS unsigned char*)lds + MISC_OFF) + 8);
;     grid.sync();
.LBB0_5:
	s_or_b64 exec, exec, s[4:5]
	v_lshrrev_b32_e32 v1, 20, v0
	v_lshrrev_b32_e32 v0, 10, v0
	v_or_b32_e32 v0, v0, v1
	s_movk_i32 s4, 0x3ff
	v_and_or_b32 v0, v0, s4, v216
	v_cmp_eq_u32_e32 vcc, 0, v0
	s_barrier
	s_and_saveexec_b64 s[4:5], vcc
	s_branch .LBB0_15
	buffer_wbl2 sc1
	s_waitcnt vmcnt(0)
	s_load_dwordx2 s[6:7], s[6:7], 0x58
	v_mov_b32_e32 v2, 0
	s_mov_b64 s[8:9], exec
	v_mbcnt_lo_u32_b32 v1, s8, 0
	v_mbcnt_hi_u32_b32 v1, s9, v1
	s_waitcnt lgkmcnt(0)
	global_load_dword v0, v2, s[6:7] offset:40
	v_cmp_eq_u32_e32 vcc, 0, v1
	s_and_saveexec_b64 s[10:11], vcc
	s_cbranch_execz .LBB0_8
	s_bcnt1_i32_b64 s8, s[8:9]
	v_mov_b32_e32 v3, s8
	global_atomic_add v3, v2, v3, s[6:7] offset:32 sc0

; __global__ void __launch_bounds__(NTHR, 2) mega_fwd(Args args) {
;     ...
;         for (int k = 0; k < upc; ++k) {
;             const int unit = vcu * upc + k; if (unit >= T / 32) break;
;             const int b = unit >> 8, t0 = (unit & 255) * 32;
;             const int row_lo = (k > 0 && t0 != 0) ? 30 : 0;
;             for (int idx = tid + row_lo * 128; idx < 62 * 128; idx += NTHR) {
;                 const int row = idx >> 7, ch8 = idx & 127, srow = t0 - 30 + row; v4u o = {0u, 0u, 0u, 0u};
;                 if (srow >= 0) { const bf16* p = CGb + (size_t)(b * SEQ + srow) * 2048 + ch8 * 8; const v4u a = *(const v4u*)p, gg = *(const v4u*)(p + 1024);
.LBB0_246:
	s_mul_i32 s14, s44, s66
	s_add_i32 s16, s22, s14
	s_cmpk_gt_i32 s16, 0x3ff
	s_mov_b64 s[14:15], -1
	s_cbranch_scc1 .LBB0_245
	s_lshl_b32 s14, s16, 5
	s_ashr_i32 s29, s16, 8
	s_and_b32 s30, s14, 0x1fe0
	s_cmp_lg_u32 s22, 0
	s_cselect_b64 s[14:15], -1, 0
	s_cmp_lg_u32 s30, 0
	s_cselect_b64 s[16:17], -1, 0
	s_and_b64 s[14:15], s[14:15], s[16:17]
	s_and_b64 s[14:15], s[14:15], exec
	s_cselect_b32 s14, 0xf00, 0
	s_cselect_b32 s17, 1, 0
	v_add_u32_e32 v74, s14, v192
	s_movk_i32 s14, 0x1f00
	v_cmp_gt_i32_e32 vcc, s14, v74
	s_and_saveexec_b64 s[14:15], vcc
	s_cbranch_execz .LBB0_252
	s_sub_i32 s31, s30, 30
	s_lshl_b32 s34, s29, 13
	s_cmp_eq_u32 s17, 1
	s_cbranch_scc1 .Lmy_glu_fast
	s_mov_b64 s[16:17], 0
	s_branch .LBB0_250

; __device__ __forceinline__ unsigned cvt_pk_bf16(float lo, float hi) { f32x2_t v = {lo, hi}; bf16x2_t b = __builtin_convertvector(v, bf16x2_t); return __builtin_bit_cast(unsigned, b); }
; __device__ __forceinline__ float bflo(unsigned w) { return __uint_as_float(w << 16); }
; __device__ __forceinline__ float bfhi(unsigned w) { return __uint_as_float(w & 0xffff0000u); }
; __device__ __forceinline__ float sigmoidf_(float x) { return __builtin_amdgcn_rcpf(1.0f + __expf(-x)); }
; #define LAS __attribute__((address_space(3)))
; __global__ void __launch_bounds__(NTHR, 2) mega_fwd(Args args) {
;     ...
;             for (int idx = tid + row_lo * 128; idx < 62 * 128; idx += NTHR) {
;                 const int row = idx >> 7, ch8 = idx & 127, srow = t0 - 30 + row; v4u o = {0u, 0u, 0u, 0u};
;                 if (srow >= 0) { const bf16* p = CGb + (size_t)(b * SEQ + srow) * 2048 + ch8 * 8; const v4u a = *(const v4u*)p, gg = *(const v4u*)(p + 1024);
;                     o.x = pg8::cvt_pk_bf16(pg8::bflo(a.x) * pg8::sigmoidf_(pg8::bflo(gg.x)), pg8::bfhi(a.x) * pg8::sigmoidf_(pg8::bfhi(gg.x)));
;                     o.y = pg8::cvt_pk_bf16(pg8::bflo(a.y) * pg8::sigmoidf_(pg8::bflo(gg.y)), pg8::bfhi(a.y) * pg8::sigmoidf_(pg8::bfhi(gg.y)));
;                     o.z = pg8::cvt_pk_bf16(pg8::bflo(a.z) * pg8::sigmoidf_(pg8::bflo(gg.z)), pg8::bfhi(a.z) * pg8::sigmoidf_(pg8::bfhi(gg.z)));
;                     o.w = pg8::cvt_pk_bf16(pg8::bflo(a.w) * pg8::sigmoidf_(pg8::bflo(gg.w)), pg8::bfhi(a.w) * pg8::sigmoidf_(pg8::bfhi(gg.w))); }
;                 *(LAS v4u*)(glu + row * 512 + ch8 * 4) = o;
;             }
.Lmy_glu_fast:
	v_ashrrev_i32_e32 v75, 7, v74
	v_add_u32_e32 v76, s31, v75
	v_add_u32_e32 v0, s34, v76
	v_ashrrev_i32_e32 v1, 31, v0
	v_lshlrev_b64 v[0:1], 12, v[0:1]
	v_lshl_add_u64 v[76:77], v[72:73], 0, v[0:1]
	s_mov_b64 s[16:17], 0x4000
	v_lshl_add_u32 v75, v75, 11, v176
	global_load_dwordx4 v[84:87], v[76:77], off
	global_load_dwordx4 v[88:91], v[76:77], off offset:2048
	v_lshl_add_u64 v[76:77], v[76:77], 0, s[16:17]
	global_load_dwordx4 v[92:95], v[76:77], off
	global_load_dwordx4 v[96:99], v[76:77], off offset:2048
	v_lshl_add_u64 v[76:77], v[76:77], 0, s[16:17]
	global_load_dwordx4 v[100:103], v[76:77], off
	global_load_dwordx4 v[104:107], v[76:77], off offset:2048
	v_lshl_add_u64 v[76:77], v[76:77], 0, s[16:17]
	global_load_dwordx4 v[108:111], v[76:77], off
	global_load_dwordx4 v[112:115], v[76:77], off offset:2048
	v_lshl_add_u64 v[76:77], v[76:77], 0, s[16:17]
	global_load_dwordx4 v[116:119], v[76:77], off
	global_load_dwordx4 v[120:123], v[76:77], off offset:2048
	v_lshl_add_u64 v[76:77], v[76:77], 0, s[16:17]
	global_load_dwordx4 v[124:127], v[76:77], off
	global_load_dwordx4 v[128:131], v[76:77], off offset:2048
	v_lshl_add_u64 v[76:77], v[76:77], 0, s[16:17]
	global_load_dwordx4 v[132:135], v[76:77], off
	global_load_dwordx4 v[136:139], v[76:77], off offset:2048
	v_lshl_add_u64 v[76:77], v[76:77], 0, s[16:17]
	global_load_dwordx4 v[140:143], v[76:77], off
	global_load_dwordx4 v[144:147], v[76:77], off offset:2048
	s_waitcnt vmcnt(14)
	v_lshlrev_b32_e32 v82, 16, v84
	v_lshlrev_b32_e32 v80, 16, v88
	v_and_b32_e32 v88, 0xffff0000, v88
	v_mul_f32_e32 v88, 0xbfb8aa3b, v88
	v_exp_f32_e32 v88, v88
	v_mul_f32_e32 v80, 0xbfb8aa3b, v80
	v_exp_f32_e32 v80, v80
	v_and_b32_e32 v83, 0xffff0000, v84
	v_add_f32_e32 v88, 1.0, v88
	v_rcp_f32_e32 v81, v88
	v_lshlrev_b32_e32 v88, 16, v89
	v_and_b32_e32 v89, 0xffff0000, v89
	v_mul_f32_e32 v88, 0xbfb8aa3b, v88
	v_mul_f32_e32 v89, 0xbfb8aa3b, v89
	v_exp_f32_e32 v88, v88
	v_exp_f32_e32 v89, v89
	v_add_f32_e32 v80, 1.0, v80
	v_rcp_f32_e32 v80, v80
	v_add_f32_e32 v88, 1.0, v88
	v_add_f32_e32 v89, 1.0, v89
	v_rcp_f32_e32 v88, v88
	v_rcp_f32_e32 v89, v89
	v_pk_mul_f32 v[80:81], v[80:81], v[82:83]
	s_nop 0
	v_cvt_pk_bf16_f32 v84, v80, v81
	v_lshlrev_b32_e32 v80, 16, v85
	v_and_b32_e32 v81, 0xffff0000, v85
	v_pk_mul_f32 v[88:89], v[88:89], v[80:81]
	v_lshlrev_b32_e32 v80, 16, v86
	v_cvt_pk_bf16_f32 v85, v88, v89
	v_lshlrev_b32_e32 v88, 16, v90
	v_and_b32_e32 v89, 0xffff0000, v90
	v_mul_f32_e32 v88, 0xbfb8aa3b, v88
	v_mul_f32_e32 v89, 0xbfb8aa3b, v89
	v_exp_f32_e32 v88, v88
	v_exp_f32_e32 v89, v89
	v_and_b32_e32 v81, 0xffff0000, v86
	v_lshlrev_b32_e32 v90, 16, v87
	v_add_f32_e32 v88, 1.0, v88
	v_add_f32_e32 v89, 1.0, v89
	v_rcp_f32_e32 v88, v88
	v_rcp_f32_e32 v89, v89
	s_nop 0
	v_pk_mul_f32 v[88:89], v[88:89], v[80:81]
	s_nop 0
	v_cvt_pk_bf16_f32 v86, v88, v89
	v_lshlrev_b32_e32 v88, 16, v91
	v_and_b32_e32 v89, 0xffff0000, v91
	v_mul_f32_e32 v88, 0xbfb8aa3b, v88
	v_mul_f32_e32 v89, 0xbfb8aa3b, v89
	v_exp_f32_e32 v88, v88
	v_exp_f32_e32 v89, v89
	v_and_b32_e32 v91, 0xffff0000, v87
	v_add_f32_e32 v88, 1.0, v88
	v_add_f32_e32 v89, 1.0, v89
	v_rcp_f32_e32 v88, v88
	v_rcp_f32_e32 v89, v89
	s_nop 0
	v_pk_mul_f32 v[88:89], v[88:89], v[90:91]
	s_nop 0
	v_cvt_pk_bf16_f32 v87, v88, v89
	ds_write_b128 v75, v[84:87]
	s_waitcnt vmcnt(12)
	v_lshlrev_b32_e32 v82, 16, v92
	v_lshlrev_b32_e32 v80, 16, v96
	v_and_b32_e32 v96, 0xffff0000, v96
	v_mul_f32_e32 v96, 0xbfb8aa3b, v96
	v_exp_f32_e32 v96, v96
	v_mul_f32_e32 v80, 0xbfb8aa3b, v80
	v_exp_f32_e32 v80, v80
	v_and_b32_e32 v83, 0xffff0000, v92
	v_add_f32_e32 v96, 1.0, v96
	v_rcp_f32_e32 v81, v96
	v_lshlrev_b32_e32 v96, 16, v97
	v_and_b32_e32 v97, 0xffff0000, v97
	v_mul_f32_e32 v96, 0xbfb8aa3b, v96
	v_mul_f32_e32 v97, 0xbfb8aa3b, v97
	v_exp_f32_e32 v96, v96
	v_exp_f32_e32 v97, v97
	v_add_f32_e32 v80, 1.0, v80
	v_rcp_f32_e32 v80, v80
	v_add_f32_e32 v96, 1.0, v96
	v_add_f32_e32 v97, 1.0, v97
	v_rcp_f32_e32 v96, v96
	v_rcp_f32_e32 v97, v97
	v_pk_mul_f32 v[80:81], v[80:81], v[82:83]
	s_nop 0
	v_cvt_pk_bf16_f32 v92, v80, v81
	v_lshlrev_b32_e32 v80, 16, v93
	v_and_b32_e32 v81, 0xffff0000, v93
	v_pk_mul_f32 v[96:97], v[96:97], v[80:81]
	v_lshlrev_b32_e32 v80, 16, v94
	v_cvt_pk_bf16_f32 v93, v96, v97
	v_lshlrev_b32_e32 v96, 16, v98
	v_and_b32_e32 v97, 0xffff0000, v98
	v_mul_f32_e32 v96, 0xbfb8aa3b, v96
	v_mul_f32_e32 v97, 0xbfb8aa3b, v97
	v_exp_f32_e32 v96, v96
	v_exp_f32_e32 v97, v97
	v_and_b32_e32 v81, 0xffff0000, v94
	v_lshlrev_b32_e32 v98, 16, v95
	v_add_f32_e32 v96, 1.0, v96
	v_add_f32_e32 v97, 1.0, v97
	v_rcp_f32_e32 v96, v96
	v_rcp_f32_e32 v97, v97
	s_nop 0
	v_pk_mul_f32 v[96:97], v[96:97], v[80:81]
	s_nop 0
	v_cvt_pk_bf16_f32 v94, v96, v97
	v_lshlrev_b32_e32 v96, 16, v99
	v_and_b32_e32 v97, 0xffff0000, v99
	v_mul_f32_e32 v96, 0xbfb8aa3b, v96
	v_mul_f32_e32 v97, 0xbfb8aa3b, v97
	v_exp_f32_e32 v96, v96
	v_exp_f32_e32 v97, v97
	v_and_b32_e32 v99, 0xffff0000, v95
	v_add_f32_e32 v96, 1.0, v96
	v_add_f32_e32 v97, 1.0, v97
	v_rcp_f32_e32 v96, v96
	v_rcp_f32_e32 v97, v97
	s_nop 0
	v_pk_mul_f32 v[96:97], v[96:97], v[98:99]
	s_nop 0
	v_cvt_pk_bf16_f32 v95, v96, v97
	ds_write_b128 v75, v[92:95] offset:8192
	s_waitcnt vmcnt(10)
; __device__ __forceinline__ unsigned cvt_pk_bf16(float lo, float hi) { f32x2_t v = {lo, hi}; bf16x2_t b = __builtin_convertvector(v, bf16x2_t); return __builtin_bit_cast(unsigned, b); }
; __device__ __forceinline__ float bflo(unsigned w) { return __uint_as_float(w << 16); }
; __device__ __forceinline__ float bfhi(unsigned w) { return __uint_as_float(w & 0xffff0000u); }
; __device__ __forceinline__ float sigmoidf_(float x) { return __builtin_amdgcn_rcpf(1.0f + __expf(-x)); }
; #define LAS __attribute__((address_space(3)))
; __global__ void __launch_bounds__(NTHR, 2) mega_fwd(Args args) {
;     ...
;             for (int idx = tid + row_lo * 128; idx < 62 * 128; idx += NTHR) {
;                 const int row = idx >> 7, ch8 = idx & 127, srow = t0 - 30 + row; v4u o = {0u, 0u, 0u, 0u};
;                 if (srow >= 0) { const bf16* p = CGb + (size_t)(b * SEQ + srow) * 2048 + ch8 * 8; const v4u a = *(const v4u*)p, gg = *(const v4u*)(p + 1024);
;                     o.x = pg8::cvt_pk_bf16(pg8::bflo(a.x) * pg8::sigmoidf_(pg8::bflo(gg.x)), pg8::bfhi(a.x) * pg8::sigmoidf_(pg8::bfhi(gg.x)));
;                     o.y = pg8::cvt_pk_bf16(pg8::bflo(a.y) * pg8::sigmoidf_(pg8::bflo(gg.y)), pg8::bfhi(a.y) * pg8::sigmoidf_(pg8::bfhi(gg.y)));
;                     o.z = pg8::cvt_pk_bf16(pg8::bflo(a.z) * pg8::sigmoidf_(pg8::bflo(gg.z)), pg8::bfhi(a.z) * pg8::sigmoidf_(pg8::bfhi(gg.z)));
;                     o.w = pg8::cvt_pk_bf16(pg8::bflo(a.w) * pg8::sigmoidf_(pg8::bflo(gg.w)), pg8::bfhi(a.w) * pg8::sigmoidf_(pg8::bfhi(gg.w))); }
;                 *(LAS v4u*)(glu + row * 512 + ch8 * 4) = o;
;             }
	v_lshlrev_b32_e32 v82, 16, v100
	v_lshlrev_b32_e32 v80, 16, v104
	v_and_b32_e32 v104, 0xffff0000, v104
	v_mul_f32_e32 v104, 0xbfb8aa3b, v104
	v_exp_f32_e32 v104, v104
	v_mul_f32_e32 v80, 0xbfb8aa3b, v80
	v_exp_f32_e32 v80, v80
	v_and_b32_e32 v83, 0xffff0000, v100
	v_add_f32_e32 v104, 1.0, v104
	v_rcp_f32_e32 v81, v104
	v_lshlrev_b32_e32 v104, 16, v105
	v_and_b32_e32 v105, 0xffff0000, v105
	v_mul_f32_e32 v104, 0xbfb8aa3b, v104
	v_mul_f32_e32 v105, 0xbfb8aa3b, v105
	v_exp_f32_e32 v104, v104
	v_exp_f32_e32 v105, v105
	v_add_f32_e32 v80, 1.0, v80
	v_rcp_f32_e32 v80, v80
	v_add_f32_e32 v104, 1.0, v104
	v_add_f32_e32 v105, 1.0, v105
	v_rcp_f32_e32 v104, v104
	v_rcp_f32_e32 v105, v105
	v_pk_mul_f32 v[80:81], v[80:81], v[82:83]
	s_nop 0
	v_cvt_pk_bf16_f32 v100, v80, v81
	v_lshlrev_b32_e32 v80, 16, v101
	v_and_b32_e32 v81, 0xffff0000, v101
	v_pk_mul_f32 v[104:105], v[104:105], v[80:81]
	v_lshlrev_b32_e32 v80, 16, v102
	v_cvt_pk_bf16_f32 v101, v104, v105
	v_lshlrev_b32_e32 v104, 16, v106
	v_and_b32_e32 v105, 0xffff0000, v106
	v_mul_f32_e32 v104, 0xbfb8aa3b, v104
	v_mul_f32_e32 v105, 0xbfb8aa3b, v105
	v_exp_f32_e32 v104, v104
	v_exp_f32_e32 v105, v105
	v_and_b32_e32 v81, 0xffff0000, v102
	v_lshlrev_b32_e32 v106, 16, v103
	v_add_f32_e32 v104, 1.0, v104
	v_add_f32_e32 v105, 1.0, v105
	v_rcp_f32_e32 v104, v104
	v_rcp_f32_e32 v105, v105
	s_nop 0
	v_pk_mul_f32 v[104:105], v[104:105], v[80:81]
	s_nop 0
	v_cvt_pk_bf16_f32 v102, v104, v105
	v_lshlrev_b32_e32 v104, 16, v107
	v_and_b32_e32 v105, 0xffff0000, v107
	v_mul_f32_e32 v104, 0xbfb8aa3b, v104
	v_mul_f32_e32 v105, 0xbfb8aa3b, v105
	v_exp_f32_e32 v104, v104
	v_exp_f32_e32 v105, v105
	v_and_b32_e32 v107, 0xffff0000, v103
	v_add_f32_e32 v104, 1.0, v104
	v_add_f32_e32 v105, 1.0, v105
	v_rcp_f32_e32 v104, v104
	v_rcp_f32_e32 v105, v105
	s_nop 0
	v_pk_mul_f32 v[104:105], v[104:105], v[106:107]
	s_nop 0
	v_cvt_pk_bf16_f32 v103, v104, v105
	ds_write_b128 v75, v[100:103] offset:16384
	s_waitcnt vmcnt(8)
	v_lshlrev_b32_e32 v82, 16, v108
	v_lshlrev_b32_e32 v80, 16, v112
	v_and_b32_e32 v112, 0xffff0000, v112
	v_mul_f32_e32 v112, 0xbfb8aa3b, v112
	v_exp_f32_e32 v112, v112
	v_mul_f32_e32 v80, 0xbfb8aa3b, v80
	v_exp_f32_e32 v80, v80
	v_and_b32_e32 v83, 0xffff0000, v108
	v_add_f32_e32 v112, 1.0, v112
	v_rcp_f32_e32 v81, v112
	v_lshlrev_b32_e32 v112, 16, v113
	v_and_b32_e32 v113, 0xffff0000, v113
	v_mul_f32_e32 v112, 0xbfb8aa3b, v112
	v_mul_f32_e32 v113, 0xbfb8aa3b, v113
	v_exp_f32_e32 v112, v112
	v_exp_f32_e32 v113, v113
	v_add_f32_e32 v80, 1.0, v80
	v_rcp_f32_e32 v80, v80
	v_add_f32_e32 v112, 1.0, v112
	v_add_f32_e32 v113, 1.0, v113
	v_rcp_f32_e32 v112, v112
	v_rcp_f32_e32 v113, v113
	v_pk_mul_f32 v[80:81], v[80:81], v[82:83]
	s_nop 0
	v_cvt_pk_bf16_f32 v108, v80, v81
	v_lshlrev_b32_e32 v80, 16, v109
	v_and_b32_e32 v81, 0xffff0000, v109
	v_pk_mul_f32 v[112:113], v[112:113], v[80:81]
	v_lshlrev_b32_e32 v80, 16, v110
	v_cvt_pk_bf16_f32 v109, v112, v113
	v_lshlrev_b32_e32 v112, 16, v114
	v_and_b32_e32 v113, 0xffff0000, v114
	v_mul_f32_e32 v112, 0xbfb8aa3b, v112
	v_mul_f32_e32 v113, 0xbfb8aa3b, v113
	v_exp_f32_e32 v112, v112
	v_exp_f32_e32 v113, v113
	v_and_b32_e32 v81, 0xffff0000, v110
	v_lshlrev_b32_e32 v114, 16, v111
	v_add_f32_e32 v112, 1.0, v112
	v_add_f32_e32 v113, 1.0, v113
	v_rcp_f32_e32 v112, v112
	v_rcp_f32_e32 v113, v113
	s_nop 0
	v_pk_mul_f32 v[112:113], v[112:113], v[80:81]
	s_nop 0
	v_cvt_pk_bf16_f32 v110, v112, v113
	v_lshlrev_b32_e32 v112, 16, v115
	v_and_b32_e32 v113, 0xffff0000, v115
	v_mul_f32_e32 v112, 0xbfb8aa3b, v112
	v_mul_f32_e32 v113, 0xbfb8aa3b, v113
	v_exp_f32_e32 v112, v112
	v_exp_f32_e32 v113, v113
	v_and_b32_e32 v115, 0xffff0000, v111
	v_add_f32_e32 v112, 1.0, v112
	v_add_f32_e32 v113, 1.0, v113
	v_rcp_f32_e32 v112, v112
	v_rcp_f32_e32 v113, v113
	s_nop 0
	v_pk_mul_f32 v[112:113], v[112:113], v[114:115]
	s_nop 0
	v_cvt_pk_bf16_f32 v111, v112, v113
	ds_write_b128 v75, v[108:111] offset:24576
	s_waitcnt vmcnt(6)
	v_lshlrev_b32_e32 v82, 16, v116
	v_lshlrev_b32_e32 v80, 16, v120
	v_and_b32_e32 v120, 0xffff0000, v120
	v_mul_f32_e32 v120, 0xbfb8aa3b, v120
	v_exp_f32_e32 v120, v120
	v_mul_f32_e32 v80, 0xbfb8aa3b, v80
	v_exp_f32_e32 v80, v80
	v_and_b32_e32 v83, 0xffff0000, v116
	v_add_f32_e32 v120, 1.0, v120
	v_rcp_f32_e32 v81, v120
	v_lshlrev_b32_e32 v120, 16, v121
	v_and_b32_e32 v121, 0xffff0000, v121
	v_mul_f32_e32 v120, 0xbfb8aa3b, v120
	v_mul_f32_e32 v121, 0xbfb8aa3b, v121
	v_exp_f32_e32 v120, v120
	v_exp_f32_e32 v121, v121
	v_add_f32_e32 v80, 1.0, v80
	v_rcp_f32_e32 v80, v80
	v_add_f32_e32 v120, 1.0, v120
	v_add_f32_e32 v121, 1.0, v121
	v_rcp_f32_e32 v120, v120
	v_rcp_f32_e32 v121, v121
	v_pk_mul_f32 v[80:81], v[80:81], v[82:83]
	s_nop 0
	v_cvt_pk_bf16_f32 v116, v80, v81
	v_lshlrev_b32_e32 v80, 16, v117
	v_and_b32_e32 v81, 0xffff0000, v117
	v_pk_mul_f32 v[120:121], v[120:121], v[80:81]
	v_lshlrev_b32_e32 v80, 16, v118
	v_cvt_pk_bf16_f32 v117, v120, v121
	v_lshlrev_b32_e32 v120, 16, v122
	v_and_b32_e32 v121, 0xffff0000, v122
	v_mul_f32_e32 v120, 0xbfb8aa3b, v120
	v_mul_f32_e32 v121, 0xbfb8aa3b, v121
	v_exp_f32_e32 v120, v120
	v_exp_f32_e32 v121, v121
	v_and_b32_e32 v81, 0xffff0000, v118
	v_lshlrev_b32_e32 v122, 16, v119
	v_add_f32_e32 v120, 1.0, v120
	v_add_f32_e32 v121, 1.0, v121
	v_rcp_f32_e32 v120, v120
	v_rcp_f32_e32 v121, v121
	s_nop 0
	v_pk_mul_f32 v[120:121], v[120:121], v[80:81]
	s_nop 0
	v_cvt_pk_bf16_f32 v118, v120, v121
	v_lshlrev_b32_e32 v120, 16, v123
	v_and_b32_e32 v121, 0xffff0000, v123
	v_mul_f32_e32 v120, 0xbfb8aa3b, v120
	v_mul_f32_e32 v121, 0xbfb8aa3b, v121
	v_exp_f32_e32 v120, v120
	v_exp_f32_e32 v121, v121
	v_and_b32_e32 v123, 0xffff0000, v119
	v_add_f32_e32 v120, 1.0, v120
	v_add_f32_e32 v121, 1.0, v121
	v_rcp_f32_e32 v120, v120
	v_rcp_f32_e32 v121, v121
	s_nop 0
	v_pk_mul_f32 v[120:121], v[120:121], v[122:123]
	s_nop 0
	v_cvt_pk_bf16_f32 v119, v120, v121
	ds_write_b128 v75, v[116:119] offset:32768
	s_waitcnt vmcnt(4)
; __device__ __forceinline__ unsigned cvt_pk_bf16(float lo, float hi) { f32x2_t v = {lo, hi}; bf16x2_t b = __builtin_convertvector(v, bf16x2_t); return __builtin_bit_cast(unsigned, b); }
; __device__ __forceinline__ float bflo(unsigned w) { return __uint_as_float(w << 16); }
; __device__ __forceinline__ float bfhi(unsigned w) { return __uint_as_float(w & 0xffff0000u); }
; __device__ __forceinline__ float sigmoidf_(float x) { return __builtin_amdgcn_rcpf(1.0f + __expf(-x)); }
; #define LAS __attribute__((address_space(3)))
; __global__ void __launch_bounds__(NTHR, 2) mega_fwd(Args args) {
;     ...
;             for (int idx = tid + row_lo * 128; idx < 62 * 128; idx += NTHR) {
;                 const int row = idx >> 7, ch8 = idx & 127, srow = t0 - 30 + row; v4u o = {0u, 0u, 0u, 0u};
;                 if (srow >= 0) { const bf16* p = CGb + (size_t)(b * SEQ + srow) * 2048 + ch8 * 8; const v4u a = *(const v4u*)p, gg = *(const v4u*)(p + 1024);
;                     o.x = pg8::cvt_pk_bf16(pg8::bflo(a.x) * pg8::sigmoidf_(pg8::bflo(gg.x)), pg8::bfhi(a.x) * pg8::sigmoidf_(pg8::bfhi(gg.x)));
;                     o.y = pg8::cvt_pk_bf16(pg8::bflo(a.y) * pg8::sigmoidf_(pg8::bflo(gg.y)), pg8::bfhi(a.y) * pg8::sigmoidf_(pg8::bfhi(gg.y)));
;                     o.z = pg8::cvt_pk_bf16(pg8::bflo(a.z) * pg8::sigmoidf_(pg8::bflo(gg.z)), pg8::bfhi(a.z) * pg8::sigmoidf_(pg8::bfhi(gg.z)));
;                     o.w = pg8::cvt_pk_bf16(pg8::bflo(a.w) * pg8::sigmoidf_(pg8::bflo(gg.w)), pg8::bfhi(a.w) * pg8::sigmoidf_(pg8::bfhi(gg.w))); }
;                 *(LAS v4u*)(glu + row * 512 + ch8 * 4) = o;
;             }
	v_lshlrev_b32_e32 v82, 16, v124
	v_lshlrev_b32_e32 v80, 16, v128
	v_and_b32_e32 v128, 0xffff0000, v128
	v_mul_f32_e32 v128, 0xbfb8aa3b, v128
	v_exp_f32_e32 v128, v128
	v_mul_f32_e32 v80, 0xbfb8aa3b, v80
	v_exp_f32_e32 v80, v80
	v_and_b32_e32 v83, 0xffff0000, v124
	v_add_f32_e32 v128, 1.0, v128
	v_rcp_f32_e32 v81, v128
	v_lshlrev_b32_e32 v128, 16, v129
	v_and_b32_e32 v129, 0xffff0000, v129
	v_mul_f32_e32 v128, 0xbfb8aa3b, v128
	v_mul_f32_e32 v129, 0xbfb8aa3b, v129
	v_exp_f32_e32 v128, v128
	v_exp_f32_e32 v129, v129
	v_add_f32_e32 v80, 1.0, v80
	v_rcp_f32_e32 v80, v80
	v_add_f32_e32 v128, 1.0, v128
	v_add_f32_e32 v129, 1.0, v129
	v_rcp_f32_e32 v128, v128
	v_rcp_f32_e32 v129, v129
	v_pk_mul_f32 v[80:81], v[80:81], v[82:83]
	s_nop 0
	v_cvt_pk_bf16_f32 v124, v80, v81
	v_lshlrev_b32_e32 v80, 16, v125
	v_and_b32_e32 v81, 0xffff0000, v125
	v_pk_mul_f32 v[128:129], v[128:129], v[80:81]
	v_lshlrev_b32_e32 v80, 16, v126
	v_cvt_pk_bf16_f32 v125, v128, v129
	v_lshlrev_b32_e32 v128, 16, v130
	v_and_b32_e32 v129, 0xffff0000, v130
	v_mul_f32_e32 v128, 0xbfb8aa3b, v128
	v_mul_f32_e32 v129, 0xbfb8aa3b, v129
	v_exp_f32_e32 v128, v128
	v_exp_f32_e32 v129, v129
	v_and_b32_e32 v81, 0xffff0000, v126
	v_lshlrev_b32_e32 v130, 16, v127
	v_add_f32_e32 v128, 1.0, v128
	v_add_f32_e32 v129, 1.0, v129
	v_rcp_f32_e32 v128, v128
	v_rcp_f32_e32 v129, v129
	s_nop 0
	v_pk_mul_f32 v[128:129], v[128:129], v[80:81]
	s_nop 0
	v_cvt_pk_bf16_f32 v126, v128, v129
	v_lshlrev_b32_e32 v128, 16, v131
	v_and_b32_e32 v129, 0xffff0000, v131
	v_mul_f32_e32 v128, 0xbfb8aa3b, v128
	v_mul_f32_e32 v129, 0xbfb8aa3b, v129
	v_exp_f32_e32 v128, v128
	v_exp_f32_e32 v129, v129
	v_and_b32_e32 v131, 0xffff0000, v127
	v_add_f32_e32 v128, 1.0, v128
	v_add_f32_e32 v129, 1.0, v129
	v_rcp_f32_e32 v128, v128
	v_rcp_f32_e32 v129, v129
	s_nop 0
	v_pk_mul_f32 v[128:129], v[128:129], v[130:131]
	s_nop 0
	v_cvt_pk_bf16_f32 v127, v128, v129
	ds_write_b128 v75, v[124:127] offset:40960
	s_waitcnt vmcnt(2)
	v_lshlrev_b32_e32 v82, 16, v132
	v_lshlrev_b32_e32 v80, 16, v136
	v_and_b32_e32 v136, 0xffff0000, v136
	v_mul_f32_e32 v136, 0xbfb8aa3b, v136
	v_exp_f32_e32 v136, v136
	v_mul_f32_e32 v80, 0xbfb8aa3b, v80
	v_exp_f32_e32 v80, v80
	v_and_b32_e32 v83, 0xffff0000, v132
	v_add_f32_e32 v136, 1.0, v136
	v_rcp_f32_e32 v81, v136
	v_lshlrev_b32_e32 v136, 16, v137
	v_and_b32_e32 v137, 0xffff0000, v137
	v_mul_f32_e32 v136, 0xbfb8aa3b, v136
	v_mul_f32_e32 v137, 0xbfb8aa3b, v137
	v_exp_f32_e32 v136, v136
	v_exp_f32_e32 v137, v137
	v_add_f32_e32 v80, 1.0, v80
	v_rcp_f32_e32 v80, v80
	v_add_f32_e32 v136, 1.0, v136
	v_add_f32_e32 v137, 1.0, v137
	v_rcp_f32_e32 v136, v136
	v_rcp_f32_e32 v137, v137
	v_pk_mul_f32 v[80:81], v[80:81], v[82:83]
	s_nop 0
	v_cvt_pk_bf16_f32 v132, v80, v81
	v_lshlrev_b32_e32 v80, 16, v133
	v_and_b32_e32 v81, 0xffff0000, v133
	v_pk_mul_f32 v[136:137], v[136:137], v[80:81]
	v_lshlrev_b32_e32 v80, 16, v134
	v_cvt_pk_bf16_f32 v133, v136, v137
	v_lshlrev_b32_e32 v136, 16, v138
	v_and_b32_e32 v137, 0xffff0000, v138
	v_mul_f32_e32 v136, 0xbfb8aa3b, v136
	v_mul_f32_e32 v137, 0xbfb8aa3b, v137
	v_exp_f32_e32 v136, v136
	v_exp_f32_e32 v137, v137
	v_and_b32_e32 v81, 0xffff0000, v134
	v_lshlrev_b32_e32 v138, 16, v135
	v_add_f32_e32 v136, 1.0, v136
	v_add_f32_e32 v137, 1.0, v137
	v_rcp_f32_e32 v136, v136
	v_rcp_f32_e32 v137, v137
	s_nop 0
	v_pk_mul_f32 v[136:137], v[136:137], v[80:81]
	s_nop 0
	v_cvt_pk_bf16_f32 v134, v136, v137
	v_lshlrev_b32_e32 v136, 16, v139
	v_and_b32_e32 v137, 0xffff0000, v139
	v_mul_f32_e32 v136, 0xbfb8aa3b, v136
	v_mul_f32_e32 v137, 0xbfb8aa3b, v137
	v_exp_f32_e32 v136, v136
	v_exp_f32_e32 v137, v137
	v_and_b32_e32 v139, 0xffff0000, v135
	v_add_f32_e32 v136, 1.0, v136
	v_add_f32_e32 v137, 1.0, v137
	v_rcp_f32_e32 v136, v136
	v_rcp_f32_e32 v137, v137
	s_nop 0
	v_pk_mul_f32 v[136:137], v[136:137], v[138:139]
	s_nop 0
	v_cvt_pk_bf16_f32 v135, v136, v137
	ds_write_b128 v75, v[132:135] offset:49152
	s_waitcnt vmcnt(0)
	v_lshlrev_b32_e32 v82, 16, v140
	v_lshlrev_b32_e32 v80, 16, v144
	v_and_b32_e32 v144, 0xffff0000, v144
	v_mul_f32_e32 v144, 0xbfb8aa3b, v144
	v_exp_f32_e32 v144, v144
	v_mul_f32_e32 v80, 0xbfb8aa3b, v80
	v_exp_f32_e32 v80, v80
	v_and_b32_e32 v83, 0xffff0000, v140
	v_add_f32_e32 v144, 1.0, v144
	v_rcp_f32_e32 v81, v144
	v_lshlrev_b32_e32 v144, 16, v145
	v_and_b32_e32 v145, 0xffff0000, v145
	v_mul_f32_e32 v144, 0xbfb8aa3b, v144
	v_mul_f32_e32 v145, 0xbfb8aa3b, v145
	v_exp_f32_e32 v144, v144
	v_exp_f32_e32 v145, v145
	v_add_f32_e32 v80, 1.0, v80
	v_rcp_f32_e32 v80, v80
	v_add_f32_e32 v144, 1.0, v144
	v_add_f32_e32 v145, 1.0, v145
	v_rcp_f32_e32 v144, v144
	v_rcp_f32_e32 v145, v145
	v_pk_mul_f32 v[80:81], v[80:81], v[82:83]
	s_nop 0
	v_cvt_pk_bf16_f32 v140, v80, v81
	v_lshlrev_b32_e32 v80, 16, v141
	v_and_b32_e32 v81, 0xffff0000, v141
	v_pk_mul_f32 v[144:145], v[144:145], v[80:81]
	v_lshlrev_b32_e32 v80, 16, v142
	v_cvt_pk_bf16_f32 v141, v144, v145
	v_lshlrev_b32_e32 v144, 16, v146
	v_and_b32_e32 v145, 0xffff0000, v146
	v_mul_f32_e32 v144, 0xbfb8aa3b, v144
	v_mul_f32_e32 v145, 0xbfb8aa3b, v145
	v_exp_f32_e32 v144, v144
	v_exp_f32_e32 v145, v145
	v_and_b32_e32 v81, 0xffff0000, v142
	v_lshlrev_b32_e32 v146, 16, v143
	v_add_f32_e32 v144, 1.0, v144
	v_add_f32_e32 v145, 1.0, v145
	v_rcp_f32_e32 v144, v144
	v_rcp_f32_e32 v145, v145
	s_nop 0
	v_pk_mul_f32 v[144:145], v[144:145], v[80:81]
	s_nop 0
	v_cvt_pk_bf16_f32 v142, v144, v145
	v_lshlrev_b32_e32 v144, 16, v147
	v_and_b32_e32 v145, 0xffff0000, v147
	v_mul_f32_e32 v144, 0xbfb8aa3b, v144
	v_mul_f32_e32 v145, 0xbfb8aa3b, v145
	v_exp_f32_e32 v144, v144
	v_exp_f32_e32 v145, v145
	v_and_b32_e32 v147, 0xffff0000, v143
	v_add_f32_e32 v144, 1.0, v144
	v_add_f32_e32 v145, 1.0, v145
	v_rcp_f32_e32 v144, v144
	v_rcp_f32_e32 v145, v145
	s_nop 0
	v_pk_mul_f32 v[144:145], v[144:145], v[146:147]
	s_nop 0
	v_cvt_pk_bf16_f32 v143, v144, v145
	ds_write_b128 v75, v[140:143] offset:57344

; #define VMW() asm volatile("s_waitcnt vmcnt(0)" ::: "memory")
; #define SLOAD_H(Kp, Vp, k0) do { S.st_v0 = load8(ROW(Vp, k0, sr)); S.st_v1 = load8(ROW(Vp, k0, 32 + sr)); S.st_k0 = load8(ROW(Kp, k0, sr)); S.st_k1 = load8(ROW(Kp, k0, 32 + sr)); } while (0)
; #define SWRITE_HK(bf) do { *(bf16x8*)(K_lds + (bf) * SHM_K + kws) = S.st_k0; *(bf16x8*)(K_lds + (bf) * SHM_K + kws + 32 * 256) = S.st_k1; } while (0)
; __device__ __forceinline__ void attn_prime(const BlockRef& cur, char* lds, Seam& S) {
;     int tid_ = threadIdx.x; asm volatile("" : "+v"(tid_));
;     const int tid = tid_, wid = __builtin_amdgcn_readfirstlane(tid >> 6), lane = tid & 63, r32 = lane & 31, hi = lane >> 5;
;     const int sr = tid >> 4, sc = (tid & 15) * 8, kws = KSWZ(sr, sc * 2); char* K_lds = lds + 2 * SHM_V;
;     for (int d0 = 0; d0 < 8; ++d0) S.qr[d0] = load8(cur.Q + (size_t)(wid * QBLK + r32) * D + d0 * 16 + hi * 8);
;     SLOAD_H(cur.K, cur.V, 0); VMW(); SWRITE_HK(0);
;     __syncthreads();
; }
; __global__ void __launch_bounds__(NTHR, 2) mega_fwd(Args args) {
;     ...
;         if (vcu < NSI) {
;             int si = vcu, sub = 0;
;     ...
;             att::BlockRef cur, nxt; MKREF(cur, si, sub);
;             att::attn_prime(cur, (char*)lds, S);
.LBB0_314:
	s_or_b64 exec, exec, s[14:15]
	s_nop 0
	s_nop 0
	s_nop 0
	s_nop 0
	s_nop 0
	s_nop 0
	s_nop 0
	s_nop 0
	s_nop 0
	s_nop 0
	s_nop 0
	s_nop 0
	s_waitcnt lgkmcnt(0)
	s_barrier
	s_movk_i32 s13, 0x100
	s_cmpk_lt_i32 s66, 0x100
	s_mov_b64 s[22:23], s[0:1]
	v_readfirstlane_b32 s24, v192
	s_mov_b64 s[20:21], s[0:1]
	s_mov_b64 s[18:19], s[0:1]
	s_mov_b64 s[14:15], s[0:1]
	s_mov_b64 s[16:17], s[0:1]
	s_cbranch_scc0 .LBB0_488
	s_load_dwordx2 s[22:23], s[22:23], 0xc8
	v_mov_b32_e32 v1, v216
	s_load_dwordx2 s[20:21], s[20:21], 0xc8
	v_mov_b32_e32 v195, 0
	s_load_dwordx2 s[18:19], s[18:19], 0xc8
	s_waitcnt lgkmcnt(0)
	s_add_u32 s25, s22, 0x2f800000
	s_addc_u32 s26, s23, 0
	s_load_dwordx2 s[14:15], s[14:15], 0xc8
	s_add_u32 s27, s20, 0x33800000
	s_addc_u32 s28, s21, 0
	s_add_u32 s30, s18, 0x37800000
	s_addc_u32 s31, s19, 0
	s_waitcnt lgkmcnt(0)
	s_add_u32 s14, s14, 0xf800000
	s_addc_u32 s15, s15, 0
	s_bfe_u32 s20, s66, 0x20004
	s_ashr_i32 s21, s66, 6
	s_lshl_b32 s18, s20, 15
	s_lshl_b32 s19, s21, 17
	s_or_b32 s18, s18, s19
	s_lshl_b32 s19, s66, 8
	s_and_b32 s19, s19, 0xf00
	s_lshl_b32 s20, s20, 14
	s_lshl_b32 s21, s21, 16
	s_xor_b32 s29, s19, 0x1f00
	s_or_b32 s20, s20, s21
	s_or_b32 s18, s18, s29
	s_or_b32 s22, s20, s29
	s_ashr_i32 s19, s18, 31
	s_ashr_i32 s23, s22, 31
	s_lshl_b64 s[18:19], s[18:19], 8
	s_ashr_i32 s21, s20, 31
	s_lshl_b64 s[22:23], s[22:23], 8
	s_add_u32 s36, s25, s22
	s_addc_u32 s37, s26, s23
	s_lshl_b64 s[20:21], s[20:21], 8
	s_add_u32 s70, s27, s20
	s_addc_u32 s71, s28, s21
	s_add_u32 s72, s30, s20
	s_addc_u32 s73, s31, s21
	s_load_dwordx2 s[16:17], s[16:17], 0xc8
	s_add_u32 s22, s14, s18
	s_addc_u32 s23, s15, s19
	v_readfirstlane_b32 s18, v1
	s_ashr_i32 s18, s18, 1
	s_movk_i32 s19, 0xffe0
	v_mov_b32_e32 v2, s18
	v_bfi_b32 v2, s19, v2, v1
	v_ashrrev_i32_e32 v3, 31, v2
	v_lshlrev_b64 v[2:3], 8, v[2:3]
	s_waitcnt vmcnt(32)
	v_lshrrev_b32_e32 v4, 1, v1
	v_lshl_add_u64 v[2:3], s[36:37], 0, v[2:3]
	v_and_b32_e32 v194, 16, v4
	v_lshl_add_u64 v[2:3], v[2:3], 0, v[194:195]
	global_load_dwordx4 v[156:159], v[2:3], off
	global_load_dwordx4 v[152:155], v[2:3], off offset:32
	global_load_dwordx4 v[148:151], v[2:3], off offset:64
	global_load_dwordx4 v[144:147], v[2:3], off offset:96
	global_load_dwordx4 v[140:143], v[2:3], off offset:128
	global_load_dwordx4 v[136:139], v[2:3], off offset:160
	global_load_dwordx4 v[132:135], v[2:3], off offset:192
	global_load_dwordx4 v[128:131], v[2:3], off offset:224
	v_ashrrev_i32_e32 v2, 4, v1
	v_lshlrev_b32_e32 v3, 4, v1
	s_movk_i32 s18, 0xf0
	v_and_b32_e32 v1, 0x70, v1
	v_and_b32_e32 v194, 0xf0, v3
	v_bitop3_b32 v1, v3, v1, s18 bitop3:0x6c
	v_ashrrev_i32_e32 v3, 31, v2
	s_waitcnt vmcnt(37)
	v_lshlrev_b32_e32 v10, 8, v2
	v_lshlrev_b64 v[2:3], 8, v[2:3]
	v_lshl_add_u64 v[4:5], s[72:73], 0, v[2:3]
	s_mov_b64 s[18:19], 0x2000
	v_lshl_add_u64 v[4:5], v[4:5], 0, v[194:195]
	v_lshl_add_u64 v[6:7], v[2:3], 0, s[18:19]
	global_load_dwordx4 v[96:99], v[4:5], off
	v_lshl_add_u64 v[4:5], s[72:73], 0, v[6:7]
	v_lshl_add_u64 v[2:3], s[70:71], 0, v[2:3]
	v_lshl_add_u64 v[4:5], v[4:5], 0, v[194:195]
	v_lshl_add_u64 v[2:3], v[2:3], 0, v[194:195]
	v_lshl_add_u64 v[6:7], s[70:71], 0, v[6:7]
	global_load_dwordx4 v[100:103], v[4:5], off
	v_lshl_add_u64 v[6:7], v[6:7], 0, v[194:195]
	global_load_dwordx4 v[2:5], v[2:3], off
	v_writelane_b32 v254, s25, 53
	global_load_dwordx4 v[6:9], v[6:7], off
	v_add3_u32 v1, 0, v10, v1
	v_and_b32_e32 v255, 0x800, v10
	v_lshrrev_b32_e32 v255, 4, v255
	v_xor_b32_e32 v1, v1, v255
	v_writelane_b32 v254, s26, 54
	s_waitcnt vmcnt(0)
	v_writelane_b32 v254, s27, 55
	s_ashr_i32 s18, s24, 3
	v_writelane_b32 v254, s28, 56
	s_and_b32 s18, s18, -8
	v_and_b32_e32 v0, 63, v192
	v_writelane_b32 v254, s30, 57
	s_cmpk_lt_i32 s18, 0x200
	v_writelane_b32 v254, s31, 58
	s_mov_b32 s48, 0
	v_bfe_u32 v193, v192, 4, 2
	s_cselect_b64 s[24:25], -1, 0
	s_mov_b32 s67, 0x41000000
	s_mov_b32 s26, 0x3e0293ee
	v_mbcnt_hi_u32_b32 v205, -1, v217
	v_lshlrev_b32_e32 v214, 2, v0
	s_mov_b32 s28, 0x3f4ccccd
	s_mov_b32 s64, 0x200000
	s_mov_b32 s65, 0x400000
	s_mov_b32 s27, 0x600000
	v_mov_b32_e32 v218, 0x358637bd
	s_mov_b32 s47, 0xf800000
	v_mov_b32_e32 v219, 0x260
	v_mov_b32_e32 v220, 0xff800000
	v_mov_b32_e32 v221, 0xf149f2ca
	s_mov_b32 s77, 0
	v_writelane_b32 v254, s18, 59
	s_waitcnt vmcnt(1)
	ds_write_b128 v1, v[2:5] offset:32768
	s_waitcnt vmcnt(0)
	ds_write_b128 v1, v[6:9] offset:40960
	v_lshlrev_b32_e32 v1, 3, v192
	v_and_b32_e32 v2, 0x78, v1
	v_lshlrev_b32_e32 v194, 1, v2
	s_waitcnt lgkmcnt(0)
	v_lshl_add_u64 v[4:5], s[16:17], 0, v[194:195]
	s_mov_b64 s[16:17], 0x17800000
	v_lshl_add_u64 v[196:197], s[14:15], 0, v[194:195]
	v_lshl_add_u64 v[198:199], v[4:5], 0, s[16:17]
	v_lshlrev_b32_e32 v215, 2, v2
	s_barrier
	s_branch .LBB0_317
